# attention epilogues (selected-branch combine, stick-breaking gate): loads of all 8 output groups issued together; UX copy halves loaded together
# speedup vs baseline: 1.0118x; 1.0118x over previous
.LBB0_667:
	s_setprio 0
	v_mov_b64_e32 v[32:33], s[84:85]
	v_mad_u64_u32 v[32:33], s[4:5], v166, s76, v[32:33]
	v_lshl_add_u64 v[34:35], v[32:33], 0, s[50:51]
	v_mad_u64_u32 v[32:33], s[4:5], v166, s29, v[32:33]
	v_lshlrev_b32_e32 v64, 1, v152
	v_sub_u32_e32 v33, v33, v166
	v_lshl_add_u64 v[34:35], v[34:35], 0, v[64:65]
	s_mov_b64 s[4:5], 0x7e01800
	v_lshl_add_u64 v[36:37], v[32:33], 0, s[50:51]
	v_lshl_add_u64 v[32:33], v[34:35], 0, s[4:5]
	v_add_co_u32_e32 v34, vcc, s66, v34
	s_mov_b64 s[4:5], 0x1a800400
	s_nop 0
	v_addc_co_u32_e32 v35, vcc, 0, v35, vcc
	global_load_dwordx2 v[34:35], v[34:35], off offset:2048
	global_load_dwordx2 v[66:67], v[32:33], off offset:16
	global_load_dwordx2 v[68:69], v[32:33], off offset:32
	global_load_dwordx2 v[70:71], v[32:33], off offset:48
	global_load_dwordx2 v[72:73], v[32:33], off offset:64
	global_load_dwordx2 v[74:75], v[32:33], off offset:80
	global_load_dwordx2 v[76:77], v[32:33], off offset:96
	global_load_dwordx2 v[78:79], v[32:33], off offset:112
	s_waitcnt vmcnt(7)
	v_lshlrev_b32_e32 v38, 16, v34
	v_and_b32_e32 v39, 0xffff0000, v34
	v_pk_mul_f32 v[16:17], v[16:17], v[38:39]
	s_nop 0
	v_cvt_pk_bf16_f32 v34, v16, v17
	v_lshlrev_b32_e32 v16, 16, v35
	v_and_b32_e32 v17, 0xffff0000, v35
	v_pk_mul_f32 v[16:17], v[18:19], v[16:17]
	v_lshl_add_u64 v[18:19], v[36:37], 0, v[64:65]
	v_cvt_pk_bf16_f32 v35, v16, v17
	v_lshl_add_u64 v[16:17], v[18:19], 0, s[4:5]
	v_add_co_u32_e32 v18, vcc, s2, v18
	s_nop 1
	v_addc_co_u32_e32 v19, vcc, 0, v19, vcc
	global_store_dwordx2 v[18:19], v[34:35], off offset:1024
	s_nop 0
	s_waitcnt vmcnt(0)
	v_lshlrev_b32_e32 v34, 16, v66
	v_and_b32_e32 v35, 0xffff0000, v66
	v_pk_mul_f32 v[20:21], v[20:21], v[34:35]
	s_nop 0
	v_cvt_pk_bf16_f32 v18, v20, v21
	v_lshlrev_b32_e32 v20, 16, v67
	v_and_b32_e32 v21, 0xffff0000, v67
	v_pk_mul_f32 v[20:21], v[22:23], v[20:21]
	s_nop 0
	v_cvt_pk_bf16_f32 v19, v20, v21
	global_store_dwordx2 v[16:17], v[18:19], off offset:16
	s_nop 0
	s_nop 0
	v_lshlrev_b32_e32 v20, 16, v68
	v_and_b32_e32 v21, 0xffff0000, v68
	v_pk_mul_f32 v[20:21], v[24:25], v[20:21]
	s_nop 0
	v_cvt_pk_bf16_f32 v18, v20, v21
	v_lshlrev_b32_e32 v20, 16, v69
	v_and_b32_e32 v21, 0xffff0000, v69
	v_pk_mul_f32 v[20:21], v[26:27], v[20:21]
	s_nop 0
	v_cvt_pk_bf16_f32 v19, v20, v21
	global_store_dwordx2 v[16:17], v[18:19], off offset:32
	s_nop 0
	s_nop 0
	v_lshlrev_b32_e32 v20, 16, v70
	v_and_b32_e32 v21, 0xffff0000, v70
	v_pk_mul_f32 v[20:21], v[28:29], v[20:21]
	s_nop 0
	v_cvt_pk_bf16_f32 v18, v20, v21
	v_lshlrev_b32_e32 v20, 16, v71
	v_and_b32_e32 v21, 0xffff0000, v71
	v_pk_mul_f32 v[20:21], v[30:31], v[20:21]
	s_nop 0
	v_cvt_pk_bf16_f32 v19, v20, v21
	global_store_dwordx2 v[16:17], v[18:19], off offset:48
	s_nop 0
	s_nop 0
	v_lshlrev_b32_e32 v20, 16, v72
	v_and_b32_e32 v21, 0xffff0000, v72
	v_lshlrev_b32_e32 v18, 16, v73
	v_and_b32_e32 v19, 0xffff0000, v73
	v_pk_mul_f32 v[0:1], v[0:1], v[20:21]
	v_pk_mul_f32 v[2:3], v[2:3], v[18:19]
	v_cvt_pk_bf16_f32 v0, v0, v1
	v_cvt_pk_bf16_f32 v1, v2, v3
	global_store_dwordx2 v[16:17], v[0:1], off offset:64
	s_nop 0
	s_nop 0
	v_lshlrev_b32_e32 v2, 16, v74
	v_and_b32_e32 v3, 0xffff0000, v74
	v_pk_mul_f32 v[2:3], v[4:5], v[2:3]
	s_nop 0
	v_cvt_pk_bf16_f32 v0, v2, v3
	v_lshlrev_b32_e32 v2, 16, v75
	v_and_b32_e32 v3, 0xffff0000, v75
	v_pk_mul_f32 v[2:3], v[6:7], v[2:3]
	s_nop 0
	v_cvt_pk_bf16_f32 v1, v2, v3
	global_store_dwordx2 v[16:17], v[0:1], off offset:80
	s_nop 0
	s_nop 0
	v_lshlrev_b32_e32 v2, 16, v76
	v_and_b32_e32 v3, 0xffff0000, v76
	v_pk_mul_f32 v[2:3], v[8:9], v[2:3]
	s_nop 0
	v_cvt_pk_bf16_f32 v0, v2, v3
	v_lshlrev_b32_e32 v2, 16, v77
	v_and_b32_e32 v3, 0xffff0000, v77
	v_pk_mul_f32 v[2:3], v[10:11], v[2:3]
	s_nop 0
	v_cvt_pk_bf16_f32 v1, v2, v3
	global_store_dwordx2 v[16:17], v[0:1], off offset:96
	s_nop 0
	s_nop 0
	v_lshlrev_b32_e32 v2, 16, v78
	v_and_b32_e32 v3, 0xffff0000, v78
	v_pk_mul_f32 v[2:3], v[12:13], v[2:3]
	s_nop 0
	v_cvt_pk_bf16_f32 v0, v2, v3
	v_lshlrev_b32_e32 v2, 16, v79
	v_and_b32_e32 v3, 0xffff0000, v79
	v_pk_mul_f32 v[2:3], v[14:15], v[2:3]
	s_nop 0
	v_cvt_pk_bf16_f32 v1, v2, v3
	global_store_dwordx2 v[16:17], v[0:1], off offset:112

.LBB0_690:
	v_lshlrev_b64 v[38:39], 8, v[166:167]
	s_setprio 0
	ds_bpermute_b32 v32, v159, v169
	v_lshlrev_b64 v[38:39], 1, v[38:39]
	v_lshl_add_u64 v[40:41], s[80:81], 0, v[38:39]
	s_mov_b32 s75, s51
	v_mov_b64_e32 v[42:43], s[84:85]
	s_waitcnt lgkmcnt(0)
	v_add_f32_e32 v32, v169, v32
	v_max_f32_e32 v32, 0xda24260, v32
	v_div_scale_f32 v33, s[4:5], v32, v32, 1.0
	v_rcp_f32_e32 v34, v33
	s_lshl_b32 s50, s8, 2
	v_lshl_add_u64 v[40:41], v[40:41], 0, s[74:75]
	v_mad_u64_u32 v[42:43], s[4:5], v166, s76, v[42:43]
	v_fma_f32 v35, -v33, v34, 1.0
	v_fmac_f32_e32 v34, v35, v34
	v_div_scale_f32 v35, vcc, 1.0, v32, 1.0
	v_mul_f32_e32 v36, v35, v34
	v_fma_f32 v37, -v33, v36, v35
	v_fmac_f32_e32 v36, v37, v34
	v_fma_f32 v33, -v33, v36, v35
	v_div_fmas_f32 v33, v33, v34, v36
	v_div_fixup_f32 v37, v33, v32, 1.0
	v_mad_u64_u32 v[32:33], s[4:5], v166, 48, s[36:37]
	v_lshlrev_b32_e32 v64, 1, v152
	v_lshl_add_u64 v[34:35], v[32:33], 0, s[50:51]
	v_lshl_add_u64 v[38:39], s[34:35], 0, v[38:39]
	v_lshl_add_u64 v[44:45], v[42:43], 0, s[74:75]
	v_lshlrev_b64 v[42:43], 11, v[166:167]
	v_lshl_add_u64 v[40:41], v[40:41], 0, v[64:65]
	global_load_dword v36, v[34:35], off
	global_load_dword v32, v[34:35], off offset:16
	v_lshl_add_u64 v[38:39], v[38:39], 0, s[74:75]
	global_load_dword v34, v[34:35], off offset:32
	v_lshl_add_u64 v[42:43], s[48:49], 0, v[42:43]
	global_load_dwordx2 v[48:49], v[40:41], off
	v_lshl_add_u64 v[44:45], v[44:45], 0, v[64:65]
	s_mov_b64 s[4:5], 0x7e00800
	s_mov_b32 s3, 0x7e00000
	v_lshl_add_u64 v[46:47], v[42:43], 0, s[74:75]
	v_lshl_add_u64 v[42:43], v[38:39], 0, v[64:65]
	v_lshl_add_u64 v[38:39], v[44:45], 0, s[4:5]
	v_add_co_u32_e32 v44, vcc, s3, v44
	global_load_dwordx2 v[50:51], v[42:43], off
	s_nop 0
	v_addc_co_u32_e32 v45, vcc, 0, v45, vcc
	global_load_dwordx2 v[44:45], v[44:45], off offset:2048
	global_load_dwordx2 v[66:67], v[40:41], off offset:16
	global_load_dwordx2 v[68:69], v[42:43], off offset:16
	global_load_dwordx2 v[70:71], v[38:39], off offset:16
	global_load_dwordx2 v[72:73], v[40:41], off offset:32
	global_load_dwordx2 v[74:75], v[42:43], off offset:32
	global_load_dwordx2 v[76:77], v[38:39], off offset:32
	global_load_dwordx2 v[78:79], v[40:41], off offset:48
	global_load_dwordx2 v[80:81], v[42:43], off offset:48
	global_load_dwordx2 v[82:83], v[38:39], off offset:48
	global_load_dwordx2 v[84:85], v[40:41], off offset:64
	global_load_dwordx2 v[86:87], v[42:43], off offset:64
	global_load_dwordx2 v[88:89], v[38:39], off offset:64
	global_load_dwordx2 v[90:91], v[40:41], off offset:80
	global_load_dwordx2 v[92:93], v[42:43], off offset:80
	global_load_dwordx2 v[94:95], v[38:39], off offset:80
	global_load_dwordx2 v[96:97], v[40:41], off offset:96
	global_load_dwordx2 v[98:99], v[42:43], off offset:96
	global_load_dwordx2 v[100:101], v[38:39], off offset:96
	global_load_dwordx2 v[102:103], v[40:41], off offset:112
	global_load_dwordx2 v[104:105], v[42:43], off offset:112
	global_load_dwordx2 v[106:107], v[38:39], off offset:112
	s_mov_b64 s[4:5], 0
	s_waitcnt vmcnt(25)
	v_mul_f32_e32 v32, v32, v37
	s_waitcnt vmcnt(23)
	v_lshlrev_b32_e32 v52, 16, v48
	v_and_b32_e32 v53, 0xffff0000, v48
	v_lshlrev_b32_e32 v48, 16, v49
	v_and_b32_e32 v49, 0xffff0000, v49
	v_pk_mul_f32 v[52:53], v[36:37], v[52:53] op_sel_hi:[0,1]
	v_pk_mul_f32 v[48:49], v[36:37], v[48:49] op_sel_hi:[0,1]
	v_pk_fma_f32 v[16:17], v[16:17], v[32:33], v[52:53] op_sel_hi:[1,0,1]
	v_pk_fma_f32 v[18:19], v[18:19], v[32:33], v[48:49] op_sel_hi:[1,0,1]
	s_waitcnt vmcnt(22)
	v_lshlrev_b32_e32 v54, 16, v50
	v_and_b32_e32 v55, 0xffff0000, v50
	v_lshlrev_b32_e32 v50, 16, v51
	v_and_b32_e32 v51, 0xffff0000, v51
	s_waitcnt vmcnt(21)
	v_lshlrev_b32_e32 v56, 16, v44
	v_and_b32_e32 v57, 0xffff0000, v44
	v_pk_fma_f32 v[16:17], v[34:35], v[54:55], v[16:17] op_sel_hi:[0,1,1]
	v_lshlrev_b32_e32 v44, 16, v45
	v_and_b32_e32 v45, 0xffff0000, v45
	v_pk_fma_f32 v[18:19], v[34:35], v[50:51], v[18:19] op_sel_hi:[0,1,1]
	v_pk_mul_f32 v[16:17], v[16:17], v[56:57]
	v_pk_mul_f32 v[18:19], v[18:19], v[44:45]
	v_cvt_pk_bf16_f32 v44, v16, v17
	v_cvt_pk_bf16_f32 v45, v18, v19
	v_lshl_add_u64 v[16:17], v[46:47], 0, v[64:65]
	global_store_dwordx2 v[16:17], v[44:45], off
	s_nop 0
	s_nop 0
	s_nop 0
	s_nop 0
	s_waitcnt vmcnt(0)
	v_lshlrev_b32_e32 v48, 16, v66
	v_and_b32_e32 v49, 0xffff0000, v66
	v_lshlrev_b32_e32 v18, 16, v67
	v_and_b32_e32 v19, 0xffff0000, v67
	v_pk_mul_f32 v[48:49], v[36:37], v[48:49] op_sel_hi:[0,1]
	v_pk_mul_f32 v[18:19], v[36:37], v[18:19] op_sel_hi:[0,1]
	s_nop 0
	v_lshlrev_b32_e32 v50, 16, v68
	v_and_b32_e32 v51, 0xffff0000, v68
	v_pk_fma_f32 v[20:21], v[20:21], v[32:33], v[48:49] op_sel_hi:[1,0,1]
	v_lshlrev_b32_e32 v44, 16, v69
	v_and_b32_e32 v45, 0xffff0000, v69
	v_pk_fma_f32 v[18:19], v[22:23], v[32:33], v[18:19] op_sel_hi:[1,0,1]
	s_nop 0
	v_lshlrev_b32_e32 v52, 16, v70
	v_and_b32_e32 v53, 0xffff0000, v70
	v_pk_fma_f32 v[20:21], v[34:35], v[50:51], v[20:21] op_sel_hi:[0,1,1]
	v_lshlrev_b32_e32 v46, 16, v71
	v_and_b32_e32 v47, 0xffff0000, v71
	v_pk_fma_f32 v[18:19], v[34:35], v[44:45], v[18:19] op_sel_hi:[0,1,1]
	v_pk_mul_f32 v[20:21], v[20:21], v[52:53]
	v_pk_mul_f32 v[18:19], v[18:19], v[46:47]
	v_cvt_pk_bf16_f32 v20, v20, v21
	v_cvt_pk_bf16_f32 v21, v18, v19
	global_store_dwordx2 v[16:17], v[20:21], off offset:16
	s_nop 0
	s_nop 0
	s_nop 0
	s_nop 0
	s_nop 0
	v_lshlrev_b32_e32 v44, 16, v72
	v_and_b32_e32 v45, 0xffff0000, v72
	v_lshlrev_b32_e32 v18, 16, v73
	v_and_b32_e32 v19, 0xffff0000, v73
	v_pk_mul_f32 v[44:45], v[36:37], v[44:45] op_sel_hi:[0,1]
	v_pk_mul_f32 v[18:19], v[36:37], v[18:19] op_sel_hi:[0,1]
	s_nop 0
	v_lshlrev_b32_e32 v46, 16, v74
	v_and_b32_e32 v47, 0xffff0000, v74
	v_pk_fma_f32 v[24:25], v[24:25], v[32:33], v[44:45] op_sel_hi:[1,0,1]
	v_lshlrev_b32_e32 v20, 16, v75
	v_and_b32_e32 v21, 0xffff0000, v75
	v_pk_fma_f32 v[18:19], v[26:27], v[32:33], v[18:19] op_sel_hi:[1,0,1]
	s_nop 0
	v_lshlrev_b32_e32 v48, 16, v76
	v_and_b32_e32 v49, 0xffff0000, v76
	v_pk_fma_f32 v[24:25], v[34:35], v[46:47], v[24:25] op_sel_hi:[0,1,1]
	v_lshlrev_b32_e32 v22, 16, v77
	v_and_b32_e32 v23, 0xffff0000, v77
	v_pk_fma_f32 v[18:19], v[34:35], v[20:21], v[18:19] op_sel_hi:[0,1,1]
	v_pk_mul_f32 v[24:25], v[24:25], v[48:49]
	v_pk_mul_f32 v[18:19], v[18:19], v[22:23]
	v_cvt_pk_bf16_f32 v20, v24, v25
	v_cvt_pk_bf16_f32 v21, v18, v19
	global_store_dwordx2 v[16:17], v[20:21], off offset:32
	s_nop 0
	s_nop 0
	s_nop 0
	s_nop 0
	s_nop 0
	v_lshlrev_b32_e32 v24, 16, v78
	v_and_b32_e32 v25, 0xffff0000, v78
	v_lshlrev_b32_e32 v18, 16, v79
	v_and_b32_e32 v19, 0xffff0000, v79
	v_pk_mul_f32 v[24:25], v[36:37], v[24:25] op_sel_hi:[0,1]
	v_pk_mul_f32 v[18:19], v[36:37], v[18:19] op_sel_hi:[0,1]
	s_nop 0
	v_lshlrev_b32_e32 v26, 16, v80
	v_and_b32_e32 v27, 0xffff0000, v80
	v_pk_fma_f32 v[24:25], v[28:29], v[32:33], v[24:25] op_sel_hi:[1,0,1]
	v_lshlrev_b32_e32 v20, 16, v81
	v_and_b32_e32 v21, 0xffff0000, v81
	v_pk_fma_f32 v[18:19], v[30:31], v[32:33], v[18:19] op_sel_hi:[1,0,1]
	s_nop 0
	v_lshlrev_b32_e32 v44, 16, v82
	v_and_b32_e32 v45, 0xffff0000, v82
	v_pk_fma_f32 v[24:25], v[34:35], v[26:27], v[24:25] op_sel_hi:[0,1,1]
	v_lshlrev_b32_e32 v22, 16, v83
	v_and_b32_e32 v23, 0xffff0000, v83
	v_pk_fma_f32 v[18:19], v[34:35], v[20:21], v[18:19] op_sel_hi:[0,1,1]
	v_pk_mul_f32 v[24:25], v[24:25], v[44:45]
	v_pk_mul_f32 v[18:19], v[18:19], v[22:23]
	v_cvt_pk_bf16_f32 v20, v24, v25
	v_cvt_pk_bf16_f32 v21, v18, v19
	global_store_dwordx2 v[16:17], v[20:21], off offset:48
	s_nop 0
	s_nop 0
	s_nop 0
	s_nop 0
	s_nop 0
	v_lshlrev_b32_e32 v24, 16, v84
	v_and_b32_e32 v25, 0xffff0000, v84
	v_lshlrev_b32_e32 v18, 16, v85
	v_and_b32_e32 v19, 0xffff0000, v85
	v_pk_mul_f32 v[24:25], v[36:37], v[24:25] op_sel_hi:[0,1]
	v_pk_mul_f32 v[18:19], v[36:37], v[18:19] op_sel_hi:[0,1]
	s_nop 0
	v_lshlrev_b32_e32 v26, 16, v86
	v_and_b32_e32 v27, 0xffff0000, v86
	v_pk_fma_f32 v[0:1], v[0:1], v[32:33], v[24:25] op_sel_hi:[1,0,1]
	v_lshlrev_b32_e32 v20, 16, v87
	v_and_b32_e32 v21, 0xffff0000, v87
	v_pk_fma_f32 v[2:3], v[2:3], v[32:33], v[18:19] op_sel_hi:[1,0,1]
	s_nop 0
	v_lshlrev_b32_e32 v28, 16, v88
	v_and_b32_e32 v29, 0xffff0000, v88
	v_pk_fma_f32 v[0:1], v[34:35], v[26:27], v[0:1] op_sel_hi:[0,1,1]
	v_lshlrev_b32_e32 v22, 16, v89
	v_and_b32_e32 v23, 0xffff0000, v89
	v_pk_fma_f32 v[2:3], v[34:35], v[20:21], v[2:3] op_sel_hi:[0,1,1]
	v_pk_mul_f32 v[0:1], v[0:1], v[28:29]
	v_pk_mul_f32 v[2:3], v[2:3], v[22:23]
	v_cvt_pk_bf16_f32 v0, v0, v1
	v_cvt_pk_bf16_f32 v1, v2, v3
	global_store_dwordx2 v[16:17], v[0:1], off offset:64
	s_nop 0
	s_nop 0
	s_nop 0
	s_nop 0
	s_nop 0
	v_lshlrev_b32_e32 v20, 16, v90
	v_and_b32_e32 v21, 0xffff0000, v90
	v_lshlrev_b32_e32 v0, 16, v91
	v_and_b32_e32 v1, 0xffff0000, v91
	v_pk_mul_f32 v[20:21], v[36:37], v[20:21] op_sel_hi:[0,1]
	v_pk_mul_f32 v[0:1], v[36:37], v[0:1] op_sel_hi:[0,1]
	s_nop 0
	v_lshlrev_b32_e32 v22, 16, v92
	v_and_b32_e32 v23, 0xffff0000, v92
	v_pk_fma_f32 v[4:5], v[4:5], v[32:33], v[20:21] op_sel_hi:[1,0,1]
	v_lshlrev_b32_e32 v2, 16, v93
	v_and_b32_e32 v3, 0xffff0000, v93
	v_pk_fma_f32 v[0:1], v[6:7], v[32:33], v[0:1] op_sel_hi:[1,0,1]
	s_nop 0
	v_lshlrev_b32_e32 v24, 16, v94
	v_and_b32_e32 v25, 0xffff0000, v94
	v_pk_fma_f32 v[4:5], v[34:35], v[22:23], v[4:5] op_sel_hi:[0,1,1]
	v_lshlrev_b32_e32 v18, 16, v95
	v_and_b32_e32 v19, 0xffff0000, v95
	v_pk_fma_f32 v[0:1], v[34:35], v[2:3], v[0:1] op_sel_hi:[0,1,1]
	v_pk_mul_f32 v[4:5], v[4:5], v[24:25]
	v_pk_mul_f32 v[0:1], v[0:1], v[18:19]
	v_cvt_pk_bf16_f32 v2, v4, v5
	v_cvt_pk_bf16_f32 v3, v0, v1
	global_store_dwordx2 v[16:17], v[2:3], off offset:80
	s_nop 0
	s_nop 0
	s_nop 0
	s_nop 0
	s_nop 0
	v_lshlrev_b32_e32 v6, 16, v96
	v_and_b32_e32 v7, 0xffff0000, v96
	v_lshlrev_b32_e32 v0, 16, v97
	v_and_b32_e32 v1, 0xffff0000, v97
	v_pk_mul_f32 v[6:7], v[36:37], v[6:7] op_sel_hi:[0,1]
	v_pk_mul_f32 v[0:1], v[36:37], v[0:1] op_sel_hi:[0,1]
	s_nop 0
	v_lshlrev_b32_e32 v18, 16, v98
	v_and_b32_e32 v19, 0xffff0000, v98
	v_pk_fma_f32 v[6:7], v[8:9], v[32:33], v[6:7] op_sel_hi:[1,0,1]
	v_lshlrev_b32_e32 v2, 16, v99
	v_and_b32_e32 v3, 0xffff0000, v99
	v_pk_fma_f32 v[0:1], v[10:11], v[32:33], v[0:1] op_sel_hi:[1,0,1]
	s_nop 0
	v_lshlrev_b32_e32 v20, 16, v100
	v_and_b32_e32 v21, 0xffff0000, v100
	v_pk_fma_f32 v[6:7], v[34:35], v[18:19], v[6:7] op_sel_hi:[0,1,1]
	v_lshlrev_b32_e32 v4, 16, v101
	v_and_b32_e32 v5, 0xffff0000, v101
	v_pk_fma_f32 v[0:1], v[34:35], v[2:3], v[0:1] op_sel_hi:[0,1,1]
	v_pk_mul_f32 v[6:7], v[6:7], v[20:21]
	v_pk_mul_f32 v[0:1], v[0:1], v[4:5]
	v_cvt_pk_bf16_f32 v2, v6, v7
	v_cvt_pk_bf16_f32 v3, v0, v1
	global_store_dwordx2 v[16:17], v[2:3], off offset:96
	s_nop 0
	s_nop 0
	s_nop 0
	s_nop 0
	s_nop 0
	v_lshlrev_b32_e32 v6, 16, v102
	v_and_b32_e32 v7, 0xffff0000, v102
	v_lshlrev_b32_e32 v2, 16, v103
	v_and_b32_e32 v3, 0xffff0000, v103
	v_pk_mul_f32 v[6:7], v[36:37], v[6:7] op_sel_hi:[0,1]
	v_pk_mul_f32 v[2:3], v[36:37], v[2:3] op_sel_hi:[0,1]
	s_nop 0
	v_lshlrev_b32_e32 v8, 16, v104
	v_and_b32_e32 v9, 0xffff0000, v104
	v_pk_fma_f32 v[6:7], v[12:13], v[32:33], v[6:7] op_sel_hi:[1,0,1]
	v_lshlrev_b32_e32 v0, 16, v105
	v_and_b32_e32 v1, 0xffff0000, v105
	v_pk_fma_f32 v[2:3], v[14:15], v[32:33], v[2:3] op_sel_hi:[1,0,1]
	s_nop 0
	v_lshlrev_b32_e32 v10, 16, v106
	v_and_b32_e32 v11, 0xffff0000, v106
	v_pk_fma_f32 v[6:7], v[34:35], v[8:9], v[6:7] op_sel_hi:[0,1,1]
	v_lshlrev_b32_e32 v4, 16, v107
	v_and_b32_e32 v5, 0xffff0000, v107
	v_pk_fma_f32 v[0:1], v[34:35], v[0:1], v[2:3] op_sel_hi:[0,1,1]
	v_pk_mul_f32 v[6:7], v[6:7], v[10:11]
	v_pk_mul_f32 v[0:1], v[0:1], v[4:5]
	v_cvt_pk_bf16_f32 v2, v6, v7
	v_cvt_pk_bf16_f32 v3, v0, v1
	global_store_dwordx2 v[16:17], v[2:3], off offset:112
